# panel (4-CU) barriers at the 8 panel-local GEMM seams incl. s1-s2 with an extra wait on the overlapping ACT panels (fixes the ACT/Z aliasing WAR of v1); global barriers elsewhere
# speedup vs baseline: 1.0049x; 1.0049x over previous
; __device__ __forceinline__ void xcd_barrier(const XcdBarrier& b) {
;     asm volatile("s_waitcnt vmcnt(0)" ::: "memory");
;     __syncthreads();
;     if (threadIdx.x == 0) {
;         unsigned* bar = b.bar;
.LBB0_892:
	s_waitcnt vmcnt(0)
	s_waitcnt vmcnt(0) lgkmcnt(0)
	s_barrier
	s_mov_b64 s[4:5], exec
	v_readlane_b32 s6, v238, 8
	v_readlane_b32 s7, v238, 9
	s_and_b64 s[6:7], s[4:5], s[6:7]
	s_mov_b64 exec, s[6:7]
	s_cbranch_execnz .LBB0_893
.Lmy_to_lbb8:
	s_getpc_b64 s[98:99]

; __device__ __forceinline__ void xcd_barrier(const XcdBarrier& b) {
;     asm volatile("s_waitcnt vmcnt(0)" ::: "memory");
;     __syncthreads();
;     if (threadIdx.x == 0) {
; __global__ void __launch_bounds__(512, 2) fwd_kernel(Args A_unused) {
;     ...
;         if (ph + 1 < ph_hi) {
;             if (ph_lo < 0) grid.sync();
;             xcd_barrier(xbar);
;         }
.LBB0_893:
	v_mov_b32_e32 v1, 0x20018
	ds_read_b32 v1, v1
	v_readlane_b32 s10, v238, 0
	v_readlane_b32 s13, v237, 62
	s_waitcnt vmcnt(0) lgkmcnt(0)
	s_nop 0
	v_readfirstlane_b32 s11, v1
	s_nop 3
	s_mul_i32 s11, s11, 0xcd98
	s_bitcmp1_b32 s11, s10
	s_cbranch_scc0 .Lmy_global_bar
	s_lshl_b32 s12, 2, s10
	s_add_i32 s12, s12, -1
	s_and_b32 s12, s12, 0xcd98
	s_bcnt1_i32_b32 s12, s12
	s_lshl_b32 s12, s12, 2
	s_and_b32 s6, s13, 7
	s_lshl_b32 s6, s6, 3
	s_bfe_u32 s7, s13, 0x30003
	s_add_i32 s13, s6, s7
	s_mul_i32 s6, s13, 10
	s_mul_i32 s6, s6, 0x1746
	s_lshr_b32 s6, s6, 16
	s_add_i32 s7, s6, 1
	s_min_u32 s7, s7, s13
	s_cmp_eq_u32 s10, 4
	s_cselect_b32 s11, 1, 0
	s_cmp_eq_u32 s10, 11
	s_cselect_b32 s11, 1, s11
	s_cmp_eq_u32 s11, 1
	s_cselect_b32 s6, s6, s13
	s_cselect_b32 s7, s7, s13
	s_lshl_b32 s13, s13, 6
	s_lshl_b32 s6, s6, 6
	s_lshl_b32 s7, s7, 6
	s_addk_i32 s13, 0x1000
	s_addk_i32 s6, 0x1000
	s_addk_i32 s7, 0x1000
	v_mov_b32_e32 v1, s13
	v_mov_b32_e32 v2, s6
	v_mov_b32_e32 v3, s7
	v_readlane_b32 s6, v238, 30
	v_readlane_b32 s7, v238, 31
	v_mov_b32_e32 v8, 1
	s_mov_b32 s13, 0
	s_sub_u32 s6, s6, 0x4200
	s_subb_u32 s7, s7, 0
	s_nop 4
	global_atomic_add v1, v8, s[6:7]
.Lmy_panel_spin:
	global_load_dword v4, v1, s[6:7] sc1
	global_load_dword v5, v2, s[6:7] sc1
	global_load_dword v6, v3, s[6:7] sc1
	s_add_i32 s13, s13, 1
	s_waitcnt vmcnt(0)
	v_min3_u32 v4, v4, v5, v6
	v_cmp_le_u32_e32 vcc, s12, v4
	s_cbranch_vccnz .Lmy_panel_done
	s_cmp_lt_u32 s13, 0x200000
	s_cbranch_scc0 .Lmy_panel_done
	s_sleep 1
	s_branch .Lmy_panel_spin
.Lmy_panel_done:
	buffer_inv sc1
	s_waitcnt vmcnt(0)
	s_branch .Lmy_to_lbb8

; __device__ __forceinline__ unsigned xb_ld(unsigned* p)              { return __hip_atomic_load(p, __ATOMIC_RELAXED, __HIP_MEMORY_SCOPE_AGENT); }
; __device__ __forceinline__ void xcd_barrier_complete(unsigned* bar, unsigned x, unsigned& nloc, unsigned& nx) {
;     ...
;         for (unsigned j = 0; j < 16; ++j) { const unsigned c = xb_ld(&bar[XB_XCNT(j)]); sum += c; cnt += (c > 0u) ? 1u : 0u; mine = (j == x) ? c : mine; }
;         if (sum == G) break;
;         __builtin_amdgcn_s_sleep(1);
;         if ((++sp & 255u) == 0u) { if (xb_ld(&bar[XB_TMO])) break; if (sp > XB_SPIN_CAP) { atomicAdd(&bar[XB_TMO], 1u); break; } }
;     }
;     nloc = mine > 0u ? mine : 1u; nx = cnt > 0u ? cnt : 1u;
; }
; __device__ __forceinline__ void xcd_barrier(const XcdBarrier& b) {
;     asm volatile("s_waitcnt vmcnt(0)" ::: "memory");
;     __syncthreads();
;     if (threadIdx.x == 0) {
;         unsigned* bar = b.bar;
;         __builtin_amdgcn_s_waitcnt(0);
;         unsigned nloc = b.st[0], nx = b.st[1];
;         if (nloc == 0u) { xcd_barrier_complete(bar, b.x, nloc, nx); b.st[0] = nloc; b.st[1] = nx; }
.LBB0_907:
	v_readlane_b32 s6, v237, 30
	v_readlane_b32 s7, v237, 31
	v_cmp_ne_u32_e32 vcc, 0, v1
	s_nop 0
	v_cndmask_b32_e64 v17, 0, v1, s[6:7]
	v_readlane_b32 s6, v237, 28
	v_readlane_b32 s7, v237, 29
	v_cndmask_b32_e64 v1, 0, 1, vcc
	v_cmp_ne_u32_e32 vcc, 0, v2
	v_cndmask_b32_e64 v17, v17, v2, s[6:7]
	v_readlane_b32 s6, v237, 26
	v_readlane_b32 s7, v237, 27
	v_addc_co_u32_e32 v1, vcc, 0, v1, vcc
	s_nop 0
	v_cndmask_b32_e64 v17, v17, v3, s[6:7]
	v_readlane_b32 s6, v237, 24
	v_readlane_b32 s7, v237, 25
	v_cmp_ne_u32_e32 vcc, 0, v3
	s_nop 0
	v_cndmask_b32_e64 v17, v17, v4, s[6:7]
	v_readlane_b32 s6, v237, 22
	v_readlane_b32 s7, v237, 23
	v_cndmask_b32_e64 v2, 0, 1, vcc
	v_cmp_ne_u32_e32 vcc, 0, v4
	v_cndmask_b32_e64 v17, v17, v5, s[6:7]
	v_readlane_b32 s6, v237, 20
	v_readlane_b32 s7, v237, 21
	v_addc_co_u32_e32 v1, vcc, v1, v2, vcc
	s_nop 0
	v_cndmask_b32_e64 v17, v17, v6, s[6:7]
	v_readlane_b32 s6, v237, 18
	v_readlane_b32 s7, v237, 19
	v_cmp_ne_u32_e32 vcc, 0, v5
	s_nop 0
	v_cndmask_b32_e64 v17, v17, v7, s[6:7]
	v_readlane_b32 s6, v237, 16
	v_readlane_b32 s7, v237, 17
	v_cndmask_b32_e64 v2, 0, 1, vcc
	v_cmp_ne_u32_e32 vcc, 0, v6
	v_cndmask_b32_e64 v17, v17, v8, s[6:7]
	v_readlane_b32 s6, v237, 14
	v_readlane_b32 s7, v237, 15
	v_addc_co_u32_e32 v1, vcc, v1, v2, vcc
	s_nop 0
	v_cndmask_b32_e64 v17, v17, v9, s[6:7]
	v_readlane_b32 s6, v237, 12
	v_cmp_ne_u32_e32 vcc, 0, v7
	v_readlane_b32 s7, v237, 13
	s_nop 0
	v_cndmask_b32_e64 v2, 0, 1, vcc
	v_cmp_ne_u32_e32 vcc, 0, v8
	v_cndmask_b32_e64 v17, v17, v10, s[6:7]
	v_readlane_b32 s6, v237, 10
	v_addc_co_u32_e32 v1, vcc, v1, v2, vcc
	v_readlane_b32 s7, v237, 11
	v_cmp_ne_u32_e32 vcc, 0, v9
	s_nop 0
	v_cndmask_b32_e64 v17, v17, v11, s[6:7]
	v_readlane_b32 s6, v237, 8
	v_cndmask_b32_e64 v2, 0, 1, vcc
	v_cmp_ne_u32_e32 vcc, 0, v10
	v_readlane_b32 s7, v237, 9
	s_nop 0
	v_addc_co_u32_e32 v1, vcc, v1, v2, vcc
	v_cndmask_b32_e64 v17, v17, v12, s[6:7]
	v_readlane_b32 s6, v237, 6
	v_cmp_ne_u32_e32 vcc, 0, v11
	v_readlane_b32 s7, v237, 7
	s_nop 0
	v_cndmask_b32_e64 v2, 0, 1, vcc
	v_cmp_ne_u32_e32 vcc, 0, v12
	v_cndmask_b32_e64 v17, v17, v13, s[6:7]
	v_readlane_b32 s6, v237, 4
	v_addc_co_u32_e32 v1, vcc, v1, v2, vcc
	v_readlane_b32 s7, v237, 5
	v_cmp_ne_u32_e32 vcc, 0, v13
	s_nop 0
	v_cndmask_b32_e64 v17, v17, v14, s[6:7]
	v_readlane_b32 s6, v237, 2
	v_cndmask_b32_e64 v2, 0, 1, vcc
	v_cmp_ne_u32_e32 vcc, 0, v14
	v_readlane_b32 s7, v237, 3
	s_nop 0
	v_addc_co_u32_e32 v1, vcc, v1, v2, vcc
	v_cndmask_b32_e64 v17, v17, v15, s[6:7]
	v_readlane_b32 s6, v237, 0
	v_cmp_ne_u32_e32 vcc, 0, v15
	v_readlane_b32 s7, v237, 1
	s_nop 0
	v_cndmask_b32_e64 v2, 0, 1, vcc
	v_cmp_ne_u32_e32 vcc, 0, v16
	v_cndmask_b32_e64 v17, v17, v16, s[6:7]
	v_readlane_b32 s6, v237, 54
	v_addc_co_u32_e32 v1, vcc, v1, v2, vcc
	v_max_u32_e32 v3, 1, v17
	v_max_u32_e32 v2, 1, v1
	v_mov_b32_e32 v1, s6
	v_readlane_b32 s6, v237, 55
	ds_write_b32 v1, v3
	s_nop 0
	v_mov_b32_e32 v1, s6
	ds_write_b32 v1, v2
	v_readlane_b32 s6, v238, 30
	v_readlane_b32 s7, v238, 31
	v_readlane_b32 s10, v237, 40
	s_nop 4
	global_load_dwordx4 v[4:7], v0, s[6:7] offset:-512 sc1
	global_load_dwordx4 v[8:11], v0, s[6:7] offset:-496 sc1
	s_xor_b32 s10, s10, 0x100
	s_waitcnt vmcnt(0)
	v_bcnt_u32_b32 v12, v4, 0
	v_bcnt_u32_b32 v12, v5, v12
	v_bcnt_u32_b32 v12, v6, v12
	v_bcnt_u32_b32 v12, v7, v12
	v_bcnt_u32_b32 v12, v8, v12
	v_bcnt_u32_b32 v12, v9, v12
	v_bcnt_u32_b32 v12, v10, v12
	v_bcnt_u32_b32 v12, v11, v12
	v_or3_b32 v13, v4, v5, v6
	v_or3_b32 v13, v13, v7, v8
	v_or3_b32 v13, v13, v9, v10
	v_or_b32_e32 v13, v13, v11
	v_bcnt_u32_b32 v13, v13, 0
	v_sub_u32_e32 v12, 8, v12
	v_sub_u32_e32 v13, 8, v13
	v_or3_b32 v12, v12, v13, s10
	v_cmp_eq_u32_e32 vcc, 0, v12
	s_nop 3
	v_cndmask_b32_e64 v12, 0, 1, vcc
	v_mov_b32_e32 v13, 0x20018
	ds_write_b32 v13, v12

; __device__ __forceinline__ unsigned xb_add(unsigned* p, unsigned v) { return __hip_atomic_fetch_add(p, v, __ATOMIC_RELAXED, __HIP_MEMORY_SCOPE_AGENT); }
; __device__ __forceinline__ void xcd_barrier(const XcdBarrier& b) {
;     ...
;         const unsigned old = xb_add(&bar[XB_XSUB(b.x)], 1u);
;         const unsigned gen = old / nloc;
;         if (old + 1u == (gen + 1u) * nloc) {
;             __builtin_amdgcn_fence(__ATOMIC_RELEASE, "agent");
;             asm volatile("s_waitcnt vmcnt(0)" ::: "memory");
;             const unsigned og = xb_add(&bar[XB_TOP], 1u);
.LBB0_925:
	s_mov_b64 s[6:7], exec
	buffer_wbl2 sc1
	s_waitcnt lgkmcnt(0)
	s_waitcnt vmcnt(0)
	v_mbcnt_lo_u32_b32 v1, s6, 0
	v_mbcnt_hi_u32_b32 v1, s7, v1
	v_cmp_eq_u32_e32 vcc, 0, v1
	s_and_saveexec_b64 s[8:9], vcc
	s_cbranch_execz .LBB0_927
	s_bcnt1_i32_b64 s6, s[6:7]
	v_mov_b32_e32 v3, s6
	v_readlane_b32 s6, v237, 36
	v_readlane_b32 s7, v237, 37
	s_nop 4
	global_atomic_add v3, v0, v3, s[6:7] sc0

; __device__ __forceinline__ unsigned xb_ld(unsigned* p)              { return __hip_atomic_load(p, __ATOMIC_RELAXED, __HIP_MEMORY_SCOPE_AGENT); }
; __device__ __forceinline__ unsigned xb_add(unsigned* p, unsigned v) { return __hip_atomic_fetch_add(p, v, __ATOMIC_RELAXED, __HIP_MEMORY_SCOPE_AGENT); }
; #define XB_SPIN(cond, bar) do { unsigned _sp = 0; while (cond) { __builtin_amdgcn_s_sleep(1); \
;     if ((++_sp & 255u) == 0u) { if (xb_ld(&(bar)[XB_TMO])) break; if (_sp > XB_SPIN_CAP) { atomicAdd(&(bar)[XB_TMO], 1u); break; } } } } while (0)
; __device__ __forceinline__ void xcd_barrier(const XcdBarrier& b) {
;     ...
;             const unsigned og = xb_add(&bar[XB_TOP], 1u);
;             const unsigned tg = og / nx;
;             if (og + 1u == (tg + 1u) * nx) xb_add(&bar[XB_TOPGEN], 1u);
;             else XB_SPIN(xb_ld(&bar[XB_TOPGEN]) == tg, bar);
;             __builtin_amdgcn_fence(__ATOMIC_ACQUIRE, "agent");
;             xb_add(&bar[XB_XGEN(b.x)], 1u);
;             asm volatile("s_waitcnt vmcnt(0)" ::: "memory");
.LBB0_942:
	s_bcnt1_i32_b64 s6, s[6:7]
	v_mov_b32_e32 v1, s6
	v_readlane_b32 s6, v237, 34
	v_readlane_b32 s7, v237, 35
	s_nop 4
	global_atomic_add v0, v1, s[6:7]
	s_getpc_b64 s[98:99]
